# row-statistics exchange (P4 and P6): the four band granules are requested together and waited for once instead of polling the partners one after the other
# speedup vs baseline: 1.0008x; 1.0008x over previous
.LBB0_114:
	s_or_b64 exec, exec, s[16:17]
	s_movk_i32 s1, 0x100
	v_cmp_gt_i32_e32 vcc, s1, v206
	s_waitcnt lgkmcnt(0)
	s_barrier
	s_and_saveexec_b64 s[16:17], vcc
	s_cbranch_execz .LBB0_91
	v_lshl_add_u32 v86, v206, 2, 0
	ds_read2st64_b32 v[10:11], v86 offset1:4
	ds_read2st64_b32 v[12:13], v86 offset0:8 offset1:12
	s_ashr_i32 s1, s0, 31
	s_lshl_b64 s[0:1], s[0:1], 13
	s_add_u32 s0, s64, s0
	v_ashrrev_i32_e32 v207, 31, v206
	s_waitcnt lgkmcnt(1)
	v_mov_b32_e32 v66, v10
	s_waitcnt lgkmcnt(0)
	v_mov_b32_e32 v67, v12
	v_mov_b32_e32 v12, v11
	s_addc_u32 s1, s65, s1
	v_pk_add_f32 v[10:11], v[66:67], v[12:13]
	v_lshl_add_u64 v[12:13], v[206:207], 3, s[0:1]
	v_add_f32_e32 v250, v10, v11
	v_lshl_add_u64 v[10:11], s[36:37], 3, v[12:13]
	s_add_i32 s0, s69, 63
	global_store_dwordx2 v[10:11], v[250:251], off sc1
	s_mov_b64 s[0:1], 0x1000
	v_lshl_add_u64 v[12:13], v[12:13], 0, s[0:1]
	s_mov_b64 s[40:41], exec
	s_mov_b32 s37, 0
.Lx6_poll:
	global_load_dwordx2 v[82:83], v[12:13], off offset:-4096 sc1
	global_load_dwordx2 v[84:85], v[12:13], off offset:-2048 sc1
	global_load_dwordx2 v[66:67], v[12:13], off sc1
	global_load_dwordx2 v[10:11], v[12:13], off offset:2048 sc1
	s_waitcnt vmcnt(0)
	v_cmp_ne_u32_e32 vcc, v83, v251
	v_cmp_ne_u32_e64 s[42:43], v85, v251
	v_cmp_ne_u32_e64 s[0:1], v67, v251
	s_or_b64 vcc, vcc, s[42:43]
	v_cmp_ne_u32_e64 s[42:43], v11, v251
	s_or_b64 s[0:1], s[0:1], s[42:43]
	s_or_b64 vcc, vcc, s[0:1]
	s_add_i32 s37, s37, 1
	s_cmp_ge_u32 s37, s80
	s_cbranch_scc1 .Lx6_done
	s_cmp_eq_u64 vcc, 0
	s_cbranch_scc1 .Lx6_done
	s_sleep 1
	s_mov_b64 exec, vcc
	s_branch .Lx6_poll
.Lx6_done:
	s_mov_b64 exec, s[40:41]
	v_mov_b32_e32 v250, v10
	v_mov_b32_e32 v10, v82
	v_mov_b32_e32 v11, v66
	v_mov_b32_e32 v66, v84
	s_branch .LBB0_90

.LBB0_215:
	s_or_b64 exec, exec, s[40:41]
	s_movk_i32 s36, 0x100
	v_cmp_gt_i32_e32 vcc, s36, v166
	s_waitcnt lgkmcnt(0)
	s_barrier
	s_and_saveexec_b64 s[40:41], vcc
	s_cbranch_execz .LBB0_192
	v_lshl_add_u32 v30, v166, 2, 0
	ds_read2st64_b32 v[2:3], v30 offset1:4
	ds_read2st64_b32 v[8:9], v30 offset0:8 offset1:12
	s_lshl_b64 s[36:37], s[42:43], 13
	s_add_u32 s36, s71, s36
	v_ashrrev_i32_e32 v167, 31, v166
	s_waitcnt lgkmcnt(1)
	v_mov_b32_e32 v16, v2
	s_waitcnt lgkmcnt(0)
	v_mov_b32_e32 v17, v8
	v_mov_b32_e32 v8, v3
	v_pk_add_f32 v[2:3], v[16:17], v[8:9]
	s_addc_u32 s37, s33, s37
	v_pk_add_f32 v[2:3], v[2:3], v[2:3] op_sel:[0,1] op_sel_hi:[1,0]
	v_lshl_add_u64 v[16:17], v[166:167], 3, s[36:37]
	s_add_i32 s36, s79, 63
	v_lshl_add_u64 v[8:9], s[44:45], 3, v[16:17]
	v_mov_b32_e32 v3, v1
	s_cmpk_gt_u32 s36, 0x7e
	global_store_dwordx2 v[8:9], v[2:3], off sc1
	s_mov_b64 s[18:19], 0x1000
	v_lshl_add_u64 v[8:9], v[16:17], 0, s[18:19]
	s_mov_b64 s[18:19], exec
	s_mov_b32 s36, 0
.Lx4_poll:
	global_load_dwordx2 v[102:103], v[16:17], off sc1
	global_load_dwordx2 v[104:105], v[16:17], off offset:2048 sc1
	global_load_dwordx2 v[106:107], v[8:9], off sc1
	global_load_dwordx2 v[108:109], v[8:9], off offset:2048 sc1
	s_waitcnt vmcnt(0)
	v_cmp_ne_u32_e32 vcc, v103, v1
	v_cmp_ne_u32_e64 s[42:43], v105, v1
	v_cmp_ne_u32_e64 s[44:45], v107, v1
	v_cmp_ne_u32_e64 s[68:69], v109, v1
	s_or_b64 vcc, vcc, s[42:43]
	s_or_b64 s[44:45], s[44:45], s[68:69]
	s_or_b64 vcc, vcc, s[44:45]
	s_add_i32 s36, s36, 1
	s_cmp_ge_u32 s36, s80
	s_cbranch_scc1 .Lx4_done
	s_cmp_eq_u64 vcc, 0
	s_cbranch_scc1 .Lx4_done
	s_sleep 1
	s_mov_b64 exec, vcc
	s_branch .Lx4_poll
.Lx4_done:
	s_mov_b64 exec, s[18:19]
	v_mov_b32_e32 v103, v104
	v_mov_b32_e32 v104, v106
	v_mov_b32_e32 v105, v108
	s_branch .LBB0_191
